# v92 + B2 decode-state items: L2 prefetch of the next item's wkv state block beside the current item's loads
# speedup vs baseline: 1.0094x; 1.0007x over previous
.LBB0_285:
	s_ashr_i32 s20, s2, 3
	s_ashr_i32 s21, s20, 31
	s_and_b32 s22, s2, 7
	s_lshl_b64 s[28:29], s[20:21], 3
	s_add_u32 s21, s28, s0
	s_addc_u32 s29, s29, s1
	s_or_b32 s28, s21, s22
	s_addk_i32 s20, 0x4000
	s_lshl_b64 s[28:29], s[28:29], 12
	s_ashr_i32 s21, s20, 31
	s_waitcnt lgkmcnt(0)
	v_lshl_add_u64 v[10:11], v[2:3], 0, s[28:29]
	s_lshl_b64 s[28:29], s[20:21], 3
	s_or_b32 s23, s28, s22
	s_mul_i32 s24, s29, 0x600
	s_mul_hi_u32 s28, s23, 0x600
	v_readlane_b32 s44, v213, 42
	s_add_i32 s24, s28, s24
	s_mulk_i32 s23, 0x600
	v_readlane_b32 s28, v214, 6
	v_lshlrev_b64 v[58:59], 2, v[10:11]
	v_readlane_b32 s54, v213, 52
	v_readlane_b32 s55, v213, 53
	v_readlane_b32 s29, v214, 7
	s_add_u32 s28, s28, s23
	v_lshl_add_u64 v[18:19], s[54:55], 0, v[58:59]
	s_addc_u32 s29, s29, s24
	s_cmpk_lt_i32 s2, 0x300
	s_cbranch_scc0 .Lb2_nodpf
	v_mov_b32_e32 v62, 0x400000
	v_mov_b32_e32 v63, 0
	v_lshl_add_u64 v[62:63], v[18:19], 0, v[62:63]
	global_load_dword v66, v[62:63], off
.Lb2_nodpf:
	s_nop 1
	global_load_dwordx4 v[10:13], v8, s[28:29] offset:256
	global_load_dwordx4 v[14:17], v[18:19], off
	s_nop 0
	global_load_dwordx4 v[18:21], v[18:19], off offset:16
	s_nop 0
	global_load_dwordx4 v[22:25], v8, s[28:29] offset:272
	global_load_dwordx4 v[26:29], v8, s[28:29] offset:1024
	global_load_dwordx4 v[30:33], v8, s[28:29] offset:1040
	global_load_dwordx4 v[34:37], v8, s[28:29] offset:512
	global_load_dwordx4 v[38:41], v8, s[28:29] offset:528
	global_load_dwordx4 v[42:45], v8, s[28:29]
	global_load_dwordx4 v[46:49], v8, s[28:29] offset:16
	v_lshl_add_u64 v[50:51], v[0:1], 2, s[28:29]
	global_load_dword v60, v[50:51], off offset:1280
	s_nop 0
	global_load_dwordx4 v[50:53], v8, s[28:29] offset:768
	global_load_dwordx4 v[54:57], v8, s[28:29] offset:784
	v_readlane_b32 s28, v214, 27
	v_readlane_b32 s29, v214, 28
	v_readlane_b32 s45, v213, 43
	v_readlane_b32 s46, v213, 44
	v_readlane_b32 s47, v213, 45
	v_readlane_b32 s48, v213, 46
	v_readlane_b32 s49, v213, 47
	v_readlane_b32 s50, v213, 48
	v_readlane_b32 s51, v213, 49
	v_readlane_b32 s52, v213, 50
	v_readlane_b32 s53, v213, 51
	v_readlane_b32 s56, v213, 54
	v_readlane_b32 s57, v213, 55
	v_readlane_b32 s58, v213, 56
	v_readlane_b32 s59, v213, 57
	s_waitcnt vmcnt(0)
	v_pk_mul_f32 v[10:11], v[14:15], v[10:11]
	v_pk_mul_f32 v[12:13], v[16:17], v[12:13]
	v_add_f32_e32 v10, v10, v11
	v_add_f32_e32 v10, v12, v10
	v_pk_mul_f32 v[22:23], v[18:19], v[22:23]
	v_add_f32_e32 v10, v13, v10
	v_mul_f32_e32 v9, v15, v27
	v_add_f32_e32 v10, v22, v10
	v_pk_mul_f32 v[24:25], v[20:21], v[24:25]
	v_fmac_f32_e32 v9, v14, v26
	v_add_f32_e32 v10, v23, v10
	v_fmac_f32_e32 v9, v16, v28
	v_add_f32_e32 v10, v24, v10
	v_fmac_f32_e32 v9, v17, v29
	v_add_f32_e32 v10, v25, v10
	v_fmac_f32_e32 v9, v18, v30
	ds_bpermute_b32 v11, v5, v10
	v_fmac_f32_e32 v9, v19, v31
	v_fmac_f32_e32 v9, v20, v32
	v_fmac_f32_e32 v9, v21, v33
	ds_bpermute_b32 v12, v5, v9
	s_waitcnt lgkmcnt(1)
	v_add_f32_e32 v10, v10, v11
	ds_bpermute_b32 v11, v6, v10
	v_lshl_add_u64 v[22:23], s[28:29], 0, v[58:59]
	s_waitcnt lgkmcnt(1)
	v_add_f32_e32 v9, v9, v12
	ds_bpermute_b32 v12, v6, v9
	s_waitcnt lgkmcnt(1)
	v_add_f32_e32 v11, v10, v11
	ds_bpermute_b32 v13, v7, v11
	s_waitcnt lgkmcnt(1)
	v_add_f32_e32 v9, v9, v12
	ds_bpermute_b32 v10, v7, v9
	s_waitcnt lgkmcnt(1)
	v_add_f32_e32 v12, v11, v13
	v_pk_mul_f32 v[24:25], v[36:37], v[12:13] op_sel_hi:[1,0]
	v_pk_mul_f32 v[26:27], v[34:35], v[12:13] op_sel_hi:[1,0]
	v_pk_mul_f32 v[28:29], v[40:41], v[12:13] op_sel_hi:[1,0]
	v_pk_mul_f32 v[12:13], v[38:39], v[12:13] op_sel_hi:[1,0]
	v_pk_fma_f32 v[26:27], v[14:15], v[42:43], v[26:27] neg_lo:[0,0,1] neg_hi:[0,0,1]
	v_pk_fma_f32 v[14:15], v[16:17], v[44:45], v[24:25] neg_lo:[0,0,1] neg_hi:[0,0,1]
	v_pk_fma_f32 v[16:17], v[18:19], v[46:47], v[12:13] neg_lo:[0,0,1] neg_hi:[0,0,1]
	v_pk_fma_f32 v[18:19], v[20:21], v[48:49], v[28:29] neg_lo:[0,0,1] neg_hi:[0,0,1]
	v_pk_fma_f32 v[14:15], v[52:53], v[60:61], v[14:15] op_sel_hi:[1,0,1]
	v_pk_fma_f32 v[12:13], v[50:51], v[60:61], v[26:27] op_sel_hi:[1,0,1]
	v_pk_fma_f32 v[18:19], v[56:57], v[60:61], v[18:19] op_sel_hi:[1,0,1]
	v_pk_fma_f32 v[16:17], v[54:55], v[60:61], v[16:17] op_sel_hi:[1,0,1]
	global_store_dwordx4 v[22:23], v[12:15], off
	global_store_dwordx4 v[22:23], v[16:19], off offset:16
	s_and_saveexec_b64 s[28:29], vcc
	s_cbranch_execz .LBB0_284
	s_lshl_b64 s[20:21], s[20:21], 11
	v_readlane_b32 s23, v214, 8
	s_add_u32 s20, s23, s20
	v_readlane_b32 s23, v214, 9
	s_addc_u32 s21, s23, s21
	s_lshl_b32 s22, s22, 8
	s_add_u32 s20, s20, s22
	s_addc_u32 s21, s21, 0
	s_waitcnt lgkmcnt(0)
	v_add_f32_e32 v9, v9, v10
	v_lshl_add_u64 v[10:11], v[0:1], 2, s[20:21]
	global_store_dword v[10:11], v9, off
	s_branch .LBB0_284
